# chain-adjacent MFMA order extended to register-rotated groups with a dependency-aware reorder (44 runs), hazard-checked statically
# baseline (speedup 1.0000x reference)
;     __host__ __device__ __forceinline__ bool next(int i, Unit& u) const { const int vv = vid + (i / 5) * G; if (vv >= 256) return false; u.pm = vv >> 2; u.pn = (vv & 3) + 4 * (i % 5); return true; }
; #define PG8_STAGE(bufoff, gbase, voff) do { _Pragma("unroll") for (int _i = 0; _i < 2; ++_i) \
;         __builtin_amdgcn_global_load_lds((const unsigned*)((const char*)(gbase) + (voff)[_i]), (PG8_LAS unsigned*)(lds + (bufoff) + ldsw + _i * 8192), 16, 0, 0); } while (0)
; #define PG8_LDA(dst, b, h) do { _Pragma("unroll") for (int m = 0; m < 4; ++m) _Pragma("unroll") for (int k = 0; k < 2; ++k) dst[m][k] = *(const PG8_LAS bf16x8*)(lds + PG8_SA(b, h) + aoff + m * 2048 + k * 1024); } while (0)
; #define PG8_LDB(dst, b, h) do { _Pragma("unroll") for (int n = 0; n < 2; ++n) _Pragma("unroll") for (int k = 0; k < 2; ++k) dst[n][k] = *(const PG8_LAS bf16x8*)(lds + PG8_SB(b, h) + boff + n * 2048 + k * 1024); } while (0)
; #define PG8_WAIT_V(n) asm volatile("s_waitcnt vmcnt(" #n ")" ::: "memory")
; #define PG8_WAIT_L(n) asm volatile("s_waitcnt lgkmcnt(" #n ")" ::: "memory")
; #define PG8_BAR __builtin_amdgcn_s_barrier()
; #define PG8_SCHED __builtin_amdgcn_sched_barrier(0)
;     ...
;         const bool has_next = S.next(ui + 1, nxt);
;         const char* nA = has_next ? (const char*)g.A + (size_t)nxt.pm * tstepA + (size_t)nxt.pn * APN + kofA : cA; const char* nB = has_next ? (const char*)g.Bt + (size_t)nxt.pn * tstepB + S.b_off(nxt) + kofB : cB;
;         for (int t = 0; t < nt; t += 2) {
;             const bool last = (t == nt - 2);
;             const char* a1 = cA + (ptrdiff_t)(t + 1) * kstepA;
;             const char* a2 = last ? nA : cA + (ptrdiff_t)(t + 2) * kstepA; const char* b2 = last ? nB : cB + (ptrdiff_t)(t + 2) * kstep;
;             const char* a3 = a2 + kstepA; const char* b3 = b2 + kstep;
;             if (last && has_next) S.a_ready(nxt);
;             if constexpr (SP2) {
;             PG8_LDB(B0, 0, 0); PG8_LDB(B1, 0, 1); PG8_SCHED; PG8_LDA(At, 0, 0); PG8_STAGE(PG8_SA(1, 1), a1 + hstepA, voffA);
;             PG8_WAIT_V(8); PG8_WAIT_L(0); PG8_BAR; PG8_MMA(0, 0, At, B0); PG8_MMA(0, 1, At, B1); PG8_BAR; PG8_SCHED;
;             PG8_LDA(At, 0, 1); PG8_STAGE(PG8_SB(0, 0), b2, voffB); PG8_STAGE(PG8_SB(0, 1), b2 + hstepB, voffB); PG8_STAGE(PG8_SA(0, 0), a2, voffA);
.LBB0_97:
	s_mov_b64 s[30:31], s[6:7]
	s_ashr_i32 s6, s14, 2
	s_and_b32 s6, s6, -8
	s_and_b32 s7, s14, 7
	s_mov_b32 s20, s58
	s_mov_b32 s21, s57
	v_cmp_lt_i64_e64 s[4:5], s[14:15], v[138:139]
	s_bfe_u32 s57, s14, 0x20003
	s_or_b32 s58, s6, s7
	s_and_b64 s[6:7], s[4:5], exec
	s_cselect_b32 s24, s58, s20
	s_cselect_b32 s6, s57, s21
	s_ashr_i32 s25, s24, 31
	s_lshl_b64 s[20:21], s[24:25], 20
	s_add_u32 s20, s2, s20
	s_addc_u32 s21, s3, s21
	s_ashr_i32 s7, s6, 31
	s_lshl_b64 s[6:7], s[6:7], 17
	s_add_u32 s20, s20, s6
	s_addc_u32 s21, s21, s7
	s_and_b64 s[28:29], s[4:5], exec
	ds_read_b128 v[0:3], v141
	ds_read_b128 v[4:7], v141 offset:1024
	ds_read_b128 v[8:11], v141 offset:2048
	ds_read_b128 v[12:15], v141 offset:3072
	ds_read_b128 v[16:19], v142
	ds_read_b128 v[20:23], v142 offset:1024
	ds_read_b128 v[24:27], v142 offset:2048
	ds_read_b128 v[28:31], v142 offset:3072
	s_cselect_b32 s29, s21, s27
	s_cselect_b32 s28, s20, s26
	s_add_u32 s25, s33, s6
	s_addc_u32 s34, s36, s7
	s_ashr_i32 s6, s24, 3
	s_ashr_i32 s7, s6, 31
	s_lshl_b64 s[6:7], s[6:7], 19
	s_add_u32 s6, s25, s6
	s_addc_u32 s7, s34, s7
	s_and_b64 s[24:25], s[4:5], exec
	s_cselect_b32 s25, s7, s31
	s_cselect_b32 s24, s6, s30
	s_add_u32 s60, s26, 0x10000
	s_addc_u32 s61, s27, 0
	s_add_u32 s34, s26, 0x18000
	s_addc_u32 s35, s27, 0
	s_add_u32 s62, s26, 0xc000
	s_addc_u32 s63, s27, 0
	s_mov_b32 m0, s46
	ds_read_b128 v[32:35], v143
	ds_read_b128 v[36:39], v143 offset:1024
	ds_read_b128 v[40:43], v143 offset:2048
	ds_read_b128 v[44:47], v143 offset:3072
	ds_read_b128 v[48:51], v143 offset:4096
	ds_read_b128 v[52:55], v143 offset:5120
	ds_read_b128 v[56:59], v143 offset:6144
	ds_read_b128 v[60:63], v143 offset:7168
	global_load_lds_dwordx4 v134, s[62:63]
	v_lshl_add_u64 v[64:65], s[62:63], 0, v[130:131]
	s_mov_b32 m0, s47
	s_nop 0
	global_load_lds_dwordx4 v[64:65], off
	s_waitcnt vmcnt(8)
	s_waitcnt lgkmcnt(0)
	s_barrier
	s_setprio 1
	s_waitcnt lgkmcnt(0)
	v_mfma_f32_16x16x32_bf16 v[64:67], v[0:3], v[32:35], 0
	v_mfma_f32_16x16x32_bf16 v[64:67], v[4:7], v[36:39], v[64:67]
	v_mfma_f32_16x16x32_bf16 v[68:71], v[8:11], v[32:35], 0
	v_mfma_f32_16x16x32_bf16 v[68:71], v[12:15], v[36:39], v[68:71]
	v_mfma_f32_16x16x32_bf16 v[72:75], v[0:3], v[40:43], 0
	v_mfma_f32_16x16x32_bf16 v[72:75], v[4:7], v[44:47], v[72:75]
	v_mfma_f32_16x16x32_bf16 v[76:79], v[8:11], v[40:43], 0
	v_mfma_f32_16x16x32_bf16 v[76:79], v[12:15], v[44:47], v[76:79]
	v_mfma_f32_16x16x32_bf16 v[80:83], v[0:3], v[48:51], 0
	v_mfma_f32_16x16x32_bf16 v[80:83], v[4:7], v[52:55], v[80:83]
	v_mfma_f32_16x16x32_bf16 v[84:87], v[8:11], v[48:51], 0
	v_mfma_f32_16x16x32_bf16 v[84:87], v[12:15], v[52:55], v[84:87]
	v_mfma_f32_16x16x32_bf16 v[88:91], v[0:3], v[56:59], 0
	v_mfma_f32_16x16x32_bf16 v[88:91], v[4:7], v[60:63], v[88:91]
	v_mfma_f32_16x16x32_bf16 v[92:95], v[8:11], v[56:59], 0
	v_mfma_f32_16x16x32_bf16 v[92:95], v[12:15], v[60:63], v[92:95]
	s_setprio 0
	s_setprio 1
	v_mfma_f32_16x16x32_bf16 v[96:99], v[16:19], v[32:35], 0
	v_mfma_f32_16x16x32_bf16 v[96:99], v[20:23], v[36:39], v[96:99]
	v_mfma_f32_16x16x32_bf16 v[32:35], v[24:27], v[32:35], 0
	v_mfma_f32_16x16x32_bf16 v[32:35], v[28:31], v[36:39], v[32:35]
	v_mfma_f32_16x16x32_bf16 v[36:39], v[16:19], v[40:43], 0
	v_mfma_f32_16x16x32_bf16 v[36:39], v[20:23], v[44:47], v[36:39]
	v_mfma_f32_16x16x32_bf16 v[40:43], v[24:27], v[40:43], 0
	v_mfma_f32_16x16x32_bf16 v[40:43], v[28:31], v[44:47], v[40:43]
	v_mfma_f32_16x16x32_bf16 v[44:47], v[16:19], v[48:51], 0
	v_mfma_f32_16x16x32_bf16 v[44:47], v[20:23], v[52:55], v[44:47]
	v_mfma_f32_16x16x32_bf16 v[48:51], v[24:27], v[48:51], 0
	v_mfma_f32_16x16x32_bf16 v[48:51], v[28:31], v[52:55], v[48:51]
	v_mfma_f32_16x16x32_bf16 v[52:55], v[16:19], v[56:59], 0
	v_mfma_f32_16x16x32_bf16 v[52:55], v[20:23], v[60:63], v[52:55]
	v_mfma_f32_16x16x32_bf16 v[56:59], v[24:27], v[56:59], 0
	v_mfma_f32_16x16x32_bf16 v[56:59], v[28:31], v[60:63], v[56:59]
	s_setprio 0
	s_barrier
	v_lshl_add_u64 v[210:211], s[30:31], 0, v[132:133]
	s_mov_b32 m0, s48
	v_lshl_add_u64 v[146:147], v[210:211], 0, s[16:17]
	v_lshl_add_u64 v[212:213], s[30:31], 0, v[128:129]
	s_add_u32 s62, s30, 0x10100
	ds_read_b128 v[60:63], v143 offset:16384
	ds_read_b128 v[100:103], v143 offset:17408
	ds_read_b128 v[104:107], v143 offset:18432
	ds_read_b128 v[108:111], v143 offset:19456
	ds_read_b128 v[112:115], v143 offset:20480
	ds_read_b128 v[116:119], v143 offset:21504
	ds_read_b128 v[120:123], v143 offset:22528
	ds_read_b128 v[124:127], v143 offset:23552
	global_load_lds_dwordx4 v[146:147], off
	v_lshl_add_u64 v[146:147], v[212:213], 0, s[16:17]
	s_mov_b32 m0, s50
	s_addc_u32 s63, s31, 0
	global_load_lds_dwordx4 v[146:147], off
	s_mov_b32 m0, s51
	s_nop 0
	global_load_lds_dwordx4 v132, s[62:63]
	s_mov_b32 m0, s52
	s_nop 0
	global_load_lds_dwordx4 v128, s[62:63]
	s_mov_b32 m0, s23
	s_nop 0
	global_load_lds_dwordx4 v134, s[60:61]
	v_lshl_add_u64 v[146:147], s[60:61], 0, v[130:131]
	s_mov_b32 m0, s37
	s_nop 0
	global_load_lds_dwordx4 v[146:147], off
	s_waitcnt vmcnt(8)
	s_waitcnt lgkmcnt(0)
	s_barrier
; #define PG8_STAGE(bufoff, gbase, voff) do { _Pragma("unroll") for (int _i = 0; _i < 2; ++_i) \
;         __builtin_amdgcn_global_load_lds((const unsigned*)((const char*)(gbase) + (voff)[_i]), (PG8_LAS unsigned*)(lds + (bufoff) + ldsw + _i * 8192), 16, 0, 0); } while (0)
; #define PG8_LDA(dst, b, h) do { _Pragma("unroll") for (int m = 0; m < 4; ++m) _Pragma("unroll") for (int k = 0; k < 2; ++k) dst[m][k] = *(const PG8_LAS bf16x8*)(lds + PG8_SA(b, h) + aoff + m * 2048 + k * 1024); } while (0)
; #define PG8_LDB(dst, b, h) do { _Pragma("unroll") for (int n = 0; n < 2; ++n) _Pragma("unroll") for (int k = 0; k < 2; ++k) dst[n][k] = *(const PG8_LAS bf16x8*)(lds + PG8_SB(b, h) + boff + n * 2048 + k * 1024); } while (0)
; #define PG8_MMA(ai, bj, At, Bt) do { __builtin_amdgcn_s_setprio(1); _Pragma("unroll") for (int m = 0; m < 4; ++m) _Pragma("unroll") for (int n = 0; n < 2; ++n) _Pragma("unroll") for (int k = 0; k < 2; ++k) \
;         acc[ai][bj][m][n] = __builtin_amdgcn_mfma_f32_16x16x32_bf16(Bt[n][k], At[m][k], acc[ai][bj][m][n], 0, 0, 0); __builtin_amdgcn_s_setprio(0); } while (0)
; #define PG8_WAIT_V(n) asm volatile("s_waitcnt vmcnt(" #n ")" ::: "memory")
; #define PG8_WAIT_L(n) asm volatile("s_waitcnt lgkmcnt(" #n ")" ::: "memory")
; #define PG8_BAR __builtin_amdgcn_s_barrier()
; #define PG8_SCHED __builtin_amdgcn_sched_barrier(0)
;     ...
;             PG8_WAIT_V(8); PG8_WAIT_L(0); PG8_BAR; PG8_MMA(1, 0, At, B0); PG8_MMA(1, 1, At, B1); PG8_BAR; PG8_SCHED;
;             PG8_LDB(B0, 1, 0); PG8_LDB(B1, 1, 1); PG8_SCHED; PG8_LDA(At, 1, 0); PG8_STAGE(PG8_SA(0, 1), a2 + hstepA, voffA);
;             PG8_WAIT_V(8); PG8_WAIT_L(0); PG8_BAR; PG8_MMA(0, 0, At, B0); PG8_MMA(0, 1, At, B1); PG8_BAR; PG8_SCHED;
	s_setprio 1
	s_waitcnt lgkmcnt(0)
	v_mfma_f32_16x16x32_bf16 v[146:149], v[0:3], v[60:63], 0
	v_mfma_f32_16x16x32_bf16 v[146:149], v[4:7], v[100:103], v[146:149]
	v_mfma_f32_16x16x32_bf16 v[154:157], v[0:3], v[104:107], 0
	v_mfma_f32_16x16x32_bf16 v[154:157], v[4:7], v[108:111], v[154:157]
	v_mfma_f32_16x16x32_bf16 v[162:165], v[0:3], v[112:115], 0
	v_mfma_f32_16x16x32_bf16 v[162:165], v[4:7], v[116:119], v[162:165]
	v_mfma_f32_16x16x32_bf16 v[0:3], v[0:3], v[120:123], 0
	v_mfma_f32_16x16x32_bf16 v[0:3], v[4:7], v[124:127], v[0:3]
	v_mfma_f32_16x16x32_bf16 v[4:7], v[8:11], v[120:123], 0
	v_mfma_f32_16x16x32_bf16 v[4:7], v[12:15], v[124:127], v[4:7]
	v_mfma_f32_16x16x32_bf16 v[150:153], v[8:11], v[60:63], 0
	v_mfma_f32_16x16x32_bf16 v[150:153], v[12:15], v[100:103], v[150:153]
	v_mfma_f32_16x16x32_bf16 v[158:161], v[8:11], v[104:107], 0
	v_mfma_f32_16x16x32_bf16 v[158:161], v[12:15], v[108:111], v[158:161]
	v_mfma_f32_16x16x32_bf16 v[166:169], v[8:11], v[112:115], 0
	v_mfma_f32_16x16x32_bf16 v[166:169], v[12:15], v[116:119], v[166:169]
	s_setprio 0
	s_setprio 1
	v_mfma_f32_16x16x32_bf16 v[8:11], v[16:19], v[60:63], 0
	v_mfma_f32_16x16x32_bf16 v[8:11], v[20:23], v[100:103], v[8:11]
	v_mfma_f32_16x16x32_bf16 v[12:15], v[24:27], v[60:63], 0
	v_mfma_f32_16x16x32_bf16 v[12:15], v[28:31], v[100:103], v[12:15]
	v_mfma_f32_16x16x32_bf16 v[60:63], v[16:19], v[104:107], 0
	v_mfma_f32_16x16x32_bf16 v[60:63], v[20:23], v[108:111], v[60:63]
	v_mfma_f32_16x16x32_bf16 v[100:103], v[24:27], v[104:107], 0
	v_mfma_f32_16x16x32_bf16 v[100:103], v[28:31], v[108:111], v[100:103]
	v_mfma_f32_16x16x32_bf16 v[104:107], v[16:19], v[112:115], 0
	v_mfma_f32_16x16x32_bf16 v[104:107], v[20:23], v[116:119], v[104:107]
	v_mfma_f32_16x16x32_bf16 v[16:19], v[16:19], v[120:123], 0
	v_mfma_f32_16x16x32_bf16 v[16:19], v[20:23], v[124:127], v[16:19]
	v_mfma_f32_16x16x32_bf16 v[108:111], v[24:27], v[112:115], 0
	v_mfma_f32_16x16x32_bf16 v[108:111], v[28:31], v[116:119], v[108:111]
	v_mfma_f32_16x16x32_bf16 v[20:23], v[24:27], v[120:123], 0
	v_mfma_f32_16x16x32_bf16 v[20:23], v[28:31], v[124:127], v[20:23]
	s_setprio 0
	s_barrier
	ds_read_b128 v[24:27], v144
	ds_read_b128 v[28:31], v144 offset:1024
	ds_read_b128 v[112:115], v144 offset:2048
	ds_read_b128 v[116:119], v144 offset:3072
	ds_read_b128 v[120:123], v145
	ds_read_b128 v[124:127], v145 offset:1024
	ds_read_b128 v[170:173], v145 offset:2048
	ds_read_b128 v[174:177], v145 offset:3072
	s_add_u32 s60, s26, 0x14000
	s_addc_u32 s61, s27, 0
	s_mov_b32 m0, s39
	ds_read_b128 v[178:181], v143 offset:32768
	ds_read_b128 v[182:185], v143 offset:33792
	ds_read_b128 v[186:189], v143 offset:34816
	ds_read_b128 v[190:193], v143 offset:35840
	ds_read_b128 v[194:197], v143 offset:36864
	ds_read_b128 v[198:201], v143 offset:37888
	ds_read_b128 v[202:205], v143 offset:38912
	ds_read_b128 v[206:209], v143 offset:39936
	global_load_lds_dwordx4 v134, s[60:61]
	v_lshl_add_u64 v[214:215], s[60:61], 0, v[130:131]
	s_mov_b32 m0, s40
	s_nop 0
	global_load_lds_dwordx4 v[214:215], off
	s_waitcnt vmcnt(8)
	s_waitcnt lgkmcnt(0)
	s_barrier
	s_setprio 1
	s_waitcnt lgkmcnt(0)
	v_mfma_f32_16x16x32_bf16 v[64:67], v[24:27], v[178:181], v[64:67]
	v_mfma_f32_16x16x32_bf16 v[64:67], v[28:31], v[182:185], v[64:67]
	v_mfma_f32_16x16x32_bf16 v[68:71], v[112:115], v[178:181], v[68:71]
	v_mfma_f32_16x16x32_bf16 v[68:71], v[116:119], v[182:185], v[68:71]
	v_mfma_f32_16x16x32_bf16 v[72:75], v[24:27], v[186:189], v[72:75]
	v_mfma_f32_16x16x32_bf16 v[72:75], v[28:31], v[190:193], v[72:75]
	v_mfma_f32_16x16x32_bf16 v[76:79], v[112:115], v[186:189], v[76:79]
	v_mfma_f32_16x16x32_bf16 v[76:79], v[116:119], v[190:193], v[76:79]
	v_mfma_f32_16x16x32_bf16 v[80:83], v[24:27], v[194:197], v[80:83]
	v_mfma_f32_16x16x32_bf16 v[80:83], v[28:31], v[198:201], v[80:83]
	v_mfma_f32_16x16x32_bf16 v[84:87], v[112:115], v[194:197], v[84:87]
	v_mfma_f32_16x16x32_bf16 v[84:87], v[116:119], v[198:201], v[84:87]
	v_mfma_f32_16x16x32_bf16 v[88:91], v[24:27], v[202:205], v[88:91]
	v_mfma_f32_16x16x32_bf16 v[88:91], v[28:31], v[206:209], v[88:91]
	v_mfma_f32_16x16x32_bf16 v[92:95], v[112:115], v[202:205], v[92:95]
	v_mfma_f32_16x16x32_bf16 v[92:95], v[116:119], v[206:209], v[92:95]
	s_setprio 0
	s_setprio 1
	v_mfma_f32_16x16x32_bf16 v[96:99], v[120:123], v[178:181], v[96:99]
	v_mfma_f32_16x16x32_bf16 v[96:99], v[124:127], v[182:185], v[96:99]
	v_mfma_f32_16x16x32_bf16 v[32:35], v[170:173], v[178:181], v[32:35]
	v_mfma_f32_16x16x32_bf16 v[32:35], v[174:177], v[182:185], v[32:35]
	v_mfma_f32_16x16x32_bf16 v[36:39], v[120:123], v[186:189], v[36:39]
	v_mfma_f32_16x16x32_bf16 v[36:39], v[124:127], v[190:193], v[36:39]
	v_mfma_f32_16x16x32_bf16 v[40:43], v[170:173], v[186:189], v[40:43]
	v_mfma_f32_16x16x32_bf16 v[40:43], v[174:177], v[190:193], v[40:43]
	v_mfma_f32_16x16x32_bf16 v[44:47], v[120:123], v[194:197], v[44:47]
	v_mfma_f32_16x16x32_bf16 v[44:47], v[124:127], v[198:201], v[44:47]
	v_mfma_f32_16x16x32_bf16 v[48:51], v[170:173], v[194:197], v[48:51]
	v_mfma_f32_16x16x32_bf16 v[48:51], v[174:177], v[198:201], v[48:51]
	v_mfma_f32_16x16x32_bf16 v[52:55], v[120:123], v[202:205], v[52:55]
	v_mfma_f32_16x16x32_bf16 v[52:55], v[124:127], v[206:209], v[52:55]
	v_mfma_f32_16x16x32_bf16 v[56:59], v[170:173], v[202:205], v[56:59]
	v_mfma_f32_16x16x32_bf16 v[56:59], v[174:177], v[206:209], v[56:59]
	s_setprio 0
	s_barrier
; #define PG8_STAGE(bufoff, gbase, voff) do { _Pragma("unroll") for (int _i = 0; _i < 2; ++_i) \
;         __builtin_amdgcn_global_load_lds((const unsigned*)((const char*)(gbase) + (voff)[_i]), (PG8_LAS unsigned*)(lds + (bufoff) + ldsw + _i * 8192), 16, 0, 0); } while (0)
; #define PG8_LDA(dst, b, h) do { _Pragma("unroll") for (int m = 0; m < 4; ++m) _Pragma("unroll") for (int k = 0; k < 2; ++k) dst[m][k] = *(const PG8_LAS bf16x8*)(lds + PG8_SA(b, h) + aoff + m * 2048 + k * 1024); } while (0)
; #define PG8_LDB(dst, b, h) do { _Pragma("unroll") for (int n = 0; n < 2; ++n) _Pragma("unroll") for (int k = 0; k < 2; ++k) dst[n][k] = *(const PG8_LAS bf16x8*)(lds + PG8_SB(b, h) + boff + n * 2048 + k * 1024); } while (0)
; #define PG8_MMA(ai, bj, At, Bt) do { __builtin_amdgcn_s_setprio(1); _Pragma("unroll") for (int m = 0; m < 4; ++m) _Pragma("unroll") for (int n = 0; n < 2; ++n) _Pragma("unroll") for (int k = 0; k < 2; ++k) \
;         acc[ai][bj][m][n] = __builtin_amdgcn_mfma_f32_16x16x32_bf16(Bt[n][k], At[m][k], acc[ai][bj][m][n], 0, 0, 0); __builtin_amdgcn_s_setprio(0); } while (0)
; #define PG8_WAIT_V(n) asm volatile("s_waitcnt vmcnt(" #n ")" ::: "memory")
; #define PG8_WAIT_L(n) asm volatile("s_waitcnt lgkmcnt(" #n ")" ::: "memory")
; #define PG8_BAR __builtin_amdgcn_s_barrier()
; #define PG8_SCHED __builtin_amdgcn_sched_barrier(0)
;     ...
;             PG8_LDB(B0, 0, 0); PG8_LDB(B1, 0, 1); PG8_SCHED; PG8_LDA(At, 0, 0); PG8_STAGE(PG8_SA(1, 1), a1 + hstepA, voffA);
;             PG8_WAIT_V(8); PG8_WAIT_L(0); PG8_BAR; PG8_MMA(0, 0, At, B0); PG8_MMA(0, 1, At, B1); PG8_BAR; PG8_SCHED;
;     ...
;             PG8_LDA(At, 1, 1); PG8_STAGE(PG8_SB(1, 0), b3, voffB); PG8_STAGE(PG8_SB(1, 1), b3 + hstepB, voffB); PG8_STAGE(PG8_SA(1, 0), a3, voffA);
;             PG8_WAIT_V(8); PG8_WAIT_L(0); PG8_BAR; PG8_MMA(1, 0, At, B0); PG8_MMA(1, 1, At, B1); PG8_BAR; PG8_SCHED;
	s_mov_b32 m0, s53
	v_lshl_add_u64 v[210:211], v[210:211], 0, s[18:19]
	s_add_u32 s30, s30, 0x10180
	ds_read_b128 v[178:181], v143 offset:49152
	ds_read_b128 v[182:185], v143 offset:50176
	ds_read_b128 v[186:189], v143 offset:51200
	ds_read_b128 v[190:193], v143 offset:52224
	ds_read_b128 v[194:197], v143 offset:53248
	ds_read_b128 v[198:201], v143 offset:54272
	ds_read_b128 v[202:205], v143 offset:55296
	ds_read_b128 v[206:209], v143 offset:56320
	global_load_lds_dwordx4 v[210:211], off
	v_lshl_add_u64 v[210:211], v[212:213], 0, s[18:19]
	s_mov_b32 m0, s54
	s_addc_u32 s31, s31, 0
	global_load_lds_dwordx4 v[210:211], off
	s_mov_b32 m0, s55
	s_nop 0
	global_load_lds_dwordx4 v132, s[30:31]
	s_mov_b32 m0, s56
	s_nop 0
	global_load_lds_dwordx4 v128, s[30:31]
	s_mov_b32 m0, s42
	s_nop 0
	global_load_lds_dwordx4 v134, s[34:35]
	s_mov_b32 m0, s43
	s_nop 0
	global_load_lds_dwordx4 v130, s[34:35]
	s_waitcnt vmcnt(8)
	s_waitcnt lgkmcnt(0)
	s_barrier
	s_setprio 1
	s_waitcnt lgkmcnt(0)
	v_mfma_f32_16x16x32_bf16 v[0:3], v[24:27], v[202:205], v[0:3]
	v_mfma_f32_16x16x32_bf16 v[0:3], v[28:31], v[206:209], v[0:3]
	v_mfma_f32_16x16x32_bf16 v[4:7], v[112:115], v[202:205], v[4:7]
	v_mfma_f32_16x16x32_bf16 v[4:7], v[116:119], v[206:209], v[4:7]
	v_mfma_f32_16x16x32_bf16 v[146:149], v[24:27], v[178:181], v[146:149]
	v_mfma_f32_16x16x32_bf16 v[146:149], v[28:31], v[182:185], v[146:149]
	v_mfma_f32_16x16x32_bf16 v[150:153], v[112:115], v[178:181], v[150:153]
	v_mfma_f32_16x16x32_bf16 v[150:153], v[116:119], v[182:185], v[150:153]
	v_mfma_f32_16x16x32_bf16 v[154:157], v[24:27], v[186:189], v[154:157]
	v_mfma_f32_16x16x32_bf16 v[154:157], v[28:31], v[190:193], v[154:157]
	v_mfma_f32_16x16x32_bf16 v[158:161], v[112:115], v[186:189], v[158:161]
	v_mfma_f32_16x16x32_bf16 v[158:161], v[116:119], v[190:193], v[158:161]
	v_mfma_f32_16x16x32_bf16 v[162:165], v[24:27], v[194:197], v[162:165]
	v_mfma_f32_16x16x32_bf16 v[162:165], v[28:31], v[198:201], v[162:165]
	v_mfma_f32_16x16x32_bf16 v[166:169], v[112:115], v[194:197], v[166:169]
	v_mfma_f32_16x16x32_bf16 v[166:169], v[116:119], v[198:201], v[166:169]
	s_setprio 0
	s_setprio 1
	v_mfma_f32_16x16x32_bf16 v[8:11], v[120:123], v[178:181], v[8:11]
	v_mfma_f32_16x16x32_bf16 v[8:11], v[124:127], v[182:185], v[8:11]
	v_mfma_f32_16x16x32_bf16 v[12:15], v[170:173], v[178:181], v[12:15]
	v_mfma_f32_16x16x32_bf16 v[12:15], v[174:177], v[182:185], v[12:15]
	v_mfma_f32_16x16x32_bf16 v[24:27], v[120:123], v[186:189], v[60:63]
	v_mfma_f32_16x16x32_bf16 v[24:27], v[124:127], v[190:193], v[24:27]
	v_mfma_f32_16x16x32_bf16 v[28:31], v[170:173], v[186:189], v[100:103]
	v_mfma_f32_16x16x32_bf16 v[28:31], v[174:177], v[190:193], v[28:31]
	v_mfma_f32_16x16x32_bf16 v[60:63], v[120:123], v[194:197], v[104:107]
	v_mfma_f32_16x16x32_bf16 v[60:63], v[124:127], v[198:201], v[60:63]
	v_mfma_f32_16x16x32_bf16 v[100:103], v[170:173], v[194:197], v[108:111]
	v_mfma_f32_16x16x32_bf16 v[100:103], v[174:177], v[198:201], v[100:103]
	v_mfma_f32_16x16x32_bf16 v[16:19], v[120:123], v[202:205], v[16:19]
	v_mfma_f32_16x16x32_bf16 v[16:19], v[124:127], v[206:209], v[16:19]
	v_mfma_f32_16x16x32_bf16 v[20:23], v[170:173], v[202:205], v[20:23]
	v_mfma_f32_16x16x32_bf16 v[20:23], v[174:177], v[206:209], v[20:23]
	s_setprio 0
	s_barrier
	ds_read_b128 v[104:107], v141
	ds_read_b128 v[108:111], v141 offset:1024
	ds_read_b128 v[112:115], v141 offset:2048
	ds_read_b128 v[116:119], v141 offset:3072
	ds_read_b128 v[120:123], v142
	ds_read_b128 v[124:127], v142 offset:1024
	ds_read_b128 v[170:173], v142 offset:2048
	ds_read_b128 v[174:177], v142 offset:3072
	s_add_u32 s30, s28, 0x8000
	s_addc_u32 s31, s29, 0
	s_add_u32 s26, s26, 0x1c000
	s_addc_u32 s27, s27, 0
	s_mov_b32 m0, s46
	ds_read_b128 v[178:181], v143
	ds_read_b128 v[182:185], v143 offset:1024
	ds_read_b128 v[186:189], v143 offset:2048
	ds_read_b128 v[190:193], v143 offset:3072
	ds_read_b128 v[194:197], v143 offset:4096
	ds_read_b128 v[198:201], v143 offset:5120
	ds_read_b128 v[202:205], v143 offset:6144
	ds_read_b128 v[206:209], v143 offset:7168
	global_load_lds_dwordx4 v134, s[26:27]
	v_lshl_add_u64 v[210:211], s[26:27], 0, v[130:131]
	s_mov_b32 m0, s47
	s_nop 0
	global_load_lds_dwordx4 v[210:211], off
	s_waitcnt vmcnt(8)
	s_waitcnt lgkmcnt(0)
	s_barrier
	s_setprio 1
	s_waitcnt lgkmcnt(0)
	v_mfma_f32_16x16x32_bf16 v[64:67], v[104:107], v[178:181], v[64:67]
	v_mfma_f32_16x16x32_bf16 v[64:67], v[108:111], v[182:185], v[64:67]
	v_mfma_f32_16x16x32_bf16 v[68:71], v[112:115], v[178:181], v[68:71]
	v_mfma_f32_16x16x32_bf16 v[68:71], v[116:119], v[182:185], v[68:71]
	v_mfma_f32_16x16x32_bf16 v[72:75], v[104:107], v[186:189], v[72:75]
	v_mfma_f32_16x16x32_bf16 v[72:75], v[108:111], v[190:193], v[72:75]
	v_mfma_f32_16x16x32_bf16 v[76:79], v[112:115], v[186:189], v[76:79]
	v_mfma_f32_16x16x32_bf16 v[76:79], v[116:119], v[190:193], v[76:79]
	v_mfma_f32_16x16x32_bf16 v[80:83], v[104:107], v[194:197], v[80:83]
	v_mfma_f32_16x16x32_bf16 v[80:83], v[108:111], v[198:201], v[80:83]
	v_mfma_f32_16x16x32_bf16 v[84:87], v[112:115], v[194:197], v[84:87]
	v_mfma_f32_16x16x32_bf16 v[84:87], v[116:119], v[198:201], v[84:87]
	v_mfma_f32_16x16x32_bf16 v[88:91], v[104:107], v[202:205], v[88:91]
	v_mfma_f32_16x16x32_bf16 v[210:213], v[108:111], v[206:209], v[88:91]
	v_mfma_f32_16x16x32_bf16 v[88:91], v[112:115], v[202:205], v[92:95]
	v_mfma_f32_16x16x32_bf16 v[214:217], v[116:119], v[206:209], v[88:91]
	s_setprio 0
	s_setprio 1
	v_mfma_f32_16x16x32_bf16 v[88:91], v[120:123], v[178:181], v[96:99]
	v_mfma_f32_16x16x32_bf16 v[96:99], v[124:127], v[182:185], v[88:91]
	v_mfma_f32_16x16x32_bf16 v[32:35], v[170:173], v[178:181], v[32:35]
	v_mfma_f32_16x16x32_bf16 v[32:35], v[174:177], v[182:185], v[32:35]
	v_mfma_f32_16x16x32_bf16 v[36:39], v[120:123], v[186:189], v[36:39]
	v_mfma_f32_16x16x32_bf16 v[36:39], v[124:127], v[190:193], v[36:39]
	v_mfma_f32_16x16x32_bf16 v[40:43], v[170:173], v[186:189], v[40:43]
	v_mfma_f32_16x16x32_bf16 v[40:43], v[174:177], v[190:193], v[40:43]
	v_mfma_f32_16x16x32_bf16 v[44:47], v[120:123], v[194:197], v[44:47]
	v_mfma_f32_16x16x32_bf16 v[44:47], v[124:127], v[198:201], v[44:47]
	v_mfma_f32_16x16x32_bf16 v[48:51], v[170:173], v[194:197], v[48:51]
	v_mfma_f32_16x16x32_bf16 v[48:51], v[174:177], v[198:201], v[48:51]
	v_mfma_f32_16x16x32_bf16 v[52:55], v[120:123], v[202:205], v[52:55]
	v_mfma_f32_16x16x32_bf16 v[52:55], v[124:127], v[206:209], v[52:55]
	v_mfma_f32_16x16x32_bf16 v[56:59], v[170:173], v[202:205], v[56:59]
	v_mfma_f32_16x16x32_bf16 v[56:59], v[174:177], v[206:209], v[56:59]
	s_setprio 0
	s_barrier
; #define PG8_STAGE(bufoff, gbase, voff) do { _Pragma("unroll") for (int _i = 0; _i < 2; ++_i) \
;         __builtin_amdgcn_global_load_lds((const unsigned*)((const char*)(gbase) + (voff)[_i]), (PG8_LAS unsigned*)(lds + (bufoff) + ldsw + _i * 8192), 16, 0, 0); } while (0)
; #define PG8_LDA(dst, b, h) do { _Pragma("unroll") for (int m = 0; m < 4; ++m) _Pragma("unroll") for (int k = 0; k < 2; ++k) dst[m][k] = *(const PG8_LAS bf16x8*)(lds + PG8_SA(b, h) + aoff + m * 2048 + k * 1024); } while (0)
; #define PG8_LDB(dst, b, h) do { _Pragma("unroll") for (int n = 0; n < 2; ++n) _Pragma("unroll") for (int k = 0; k < 2; ++k) dst[n][k] = *(const PG8_LAS bf16x8*)(lds + PG8_SB(b, h) + boff + n * 2048 + k * 1024); } while (0)
; #define PG8_MMA(ai, bj, At, Bt) do { __builtin_amdgcn_s_setprio(1); _Pragma("unroll") for (int m = 0; m < 4; ++m) _Pragma("unroll") for (int n = 0; n < 2; ++n) _Pragma("unroll") for (int k = 0; k < 2; ++k) \
;         acc[ai][bj][m][n] = __builtin_amdgcn_mfma_f32_16x16x32_bf16(Bt[n][k], At[m][k], acc[ai][bj][m][n], 0, 0, 0); __builtin_amdgcn_s_setprio(0); } while (0)
; #define PG8_WAIT_V(n) asm volatile("s_waitcnt vmcnt(" #n ")" ::: "memory")
; #define PG8_WAIT_L(n) asm volatile("s_waitcnt lgkmcnt(" #n ")" ::: "memory")
; #define PG8_BAR __builtin_amdgcn_s_barrier()
; #define PG8_SCHED __builtin_amdgcn_sched_barrier(0)
;     ...
;             PG8_LDA(At, 0, 1); PG8_STAGE(PG8_SB(0, 0), b2, voffB); PG8_STAGE(PG8_SB(0, 1), b2 + hstepB, voffB); PG8_STAGE(PG8_SA(0, 0), a2, voffA);
;             PG8_WAIT_V(8); PG8_WAIT_L(0); PG8_BAR; PG8_MMA(1, 0, At, B0); PG8_MMA(1, 1, At, B1); PG8_BAR; PG8_SCHED;
;             PG8_LDB(B0, 1, 0); PG8_LDB(B1, 1, 1); PG8_SCHED; PG8_LDA(At, 1, 0); PG8_STAGE(PG8_SA(0, 1), a2 + hstepA, voffA);
;             PG8_WAIT_V(8); PG8_WAIT_L(0); PG8_BAR; PG8_MMA(0, 0, At, B0); PG8_MMA(0, 1, At, B1); PG8_BAR; PG8_SCHED;
	s_mov_b32 m0, s48
	v_lshl_add_u64 v[246:247], s[24:25], 0, v[132:133]
	s_add_u32 s26, s24, 0x10000
	ds_read_b128 v[88:91], v143 offset:16384
	ds_read_b128 v[92:95], v143 offset:17408
	ds_read_b128 v[178:181], v143 offset:18432
	ds_read_b128 v[182:185], v143 offset:19456
	ds_read_b128 v[186:189], v143 offset:20480
	ds_read_b128 v[190:193], v143 offset:21504
	ds_read_b128 v[194:197], v143 offset:22528
	ds_read_b128 v[198:201], v143 offset:23552
	global_load_lds_dwordx4 v[246:247], off
	v_lshl_add_u64 v[248:249], s[24:25], 0, v[128:129]
	s_mov_b32 m0, s50
	s_addc_u32 s27, s25, 0
	global_load_lds_dwordx4 v[248:249], off
	s_mov_b32 m0, s51
	s_nop 0
	global_load_lds_dwordx4 v132, s[26:27]
	s_mov_b32 m0, s52
	s_nop 0
	global_load_lds_dwordx4 v128, s[26:27]
	s_mov_b32 m0, s23
	s_nop 0
	global_load_lds_dwordx4 v134, s[28:29]
	v_lshl_add_u64 v[202:203], s[28:29], 0, v[130:131]
	s_mov_b32 m0, s37
	s_nop 0
	global_load_lds_dwordx4 v[202:203], off
	s_waitcnt vmcnt(8)
	s_waitcnt lgkmcnt(0)
	s_barrier
	s_setprio 1
	s_waitcnt lgkmcnt(0)
	v_mfma_f32_16x16x32_bf16 v[0:3], v[104:107], v[194:197], v[0:3]
	v_mfma_f32_16x16x32_bf16 v[0:3], v[108:111], v[198:201], v[0:3]
	v_mfma_f32_16x16x32_bf16 v[4:7], v[112:115], v[194:197], v[4:7]
	v_mfma_f32_16x16x32_bf16 v[4:7], v[116:119], v[198:201], v[4:7]
	v_mfma_f32_16x16x32_bf16 v[146:149], v[104:107], v[88:91], v[146:149]
	v_mfma_f32_16x16x32_bf16 v[146:149], v[108:111], v[92:95], v[146:149]
	v_mfma_f32_16x16x32_bf16 v[150:153], v[112:115], v[88:91], v[150:153]
	v_mfma_f32_16x16x32_bf16 v[150:153], v[116:119], v[92:95], v[150:153]
	v_mfma_f32_16x16x32_bf16 v[154:157], v[104:107], v[178:181], v[154:157]
	v_mfma_f32_16x16x32_bf16 v[154:157], v[108:111], v[182:185], v[154:157]
	v_mfma_f32_16x16x32_bf16 v[158:161], v[112:115], v[178:181], v[158:161]
	v_mfma_f32_16x16x32_bf16 v[158:161], v[116:119], v[182:185], v[158:161]
	v_mfma_f32_16x16x32_bf16 v[162:165], v[104:107], v[186:189], v[162:165]
	v_mfma_f32_16x16x32_bf16 v[162:165], v[108:111], v[190:193], v[162:165]
	v_mfma_f32_16x16x32_bf16 v[166:169], v[112:115], v[186:189], v[166:169]
	v_mfma_f32_16x16x32_bf16 v[166:169], v[116:119], v[190:193], v[166:169]
	s_setprio 0
	s_setprio 1
	v_mfma_f32_16x16x32_bf16 v[8:11], v[120:123], v[88:91], v[8:11]
	v_mfma_f32_16x16x32_bf16 v[202:205], v[124:127], v[92:95], v[8:11]
	v_mfma_f32_16x16x32_bf16 v[8:11], v[170:173], v[88:91], v[12:15]
	v_mfma_f32_16x16x32_bf16 v[206:209], v[174:177], v[92:95], v[8:11]
	v_mfma_f32_16x16x32_bf16 v[8:11], v[120:123], v[178:181], v[24:27]
	v_mfma_f32_16x16x32_bf16 v[218:221], v[124:127], v[182:185], v[8:11]
	v_mfma_f32_16x16x32_bf16 v[8:11], v[170:173], v[178:181], v[28:31]
	v_mfma_f32_16x16x32_bf16 v[178:181], v[174:177], v[182:185], v[8:11]
	v_mfma_f32_16x16x32_bf16 v[8:11], v[120:123], v[186:189], v[60:63]
	v_mfma_f32_16x16x32_bf16 v[182:185], v[124:127], v[190:193], v[8:11]
	v_mfma_f32_16x16x32_bf16 v[8:11], v[170:173], v[186:189], v[100:103]
	v_mfma_f32_16x16x32_bf16 v[186:189], v[174:177], v[190:193], v[8:11]
	v_mfma_f32_16x16x32_bf16 v[8:11], v[120:123], v[194:197], v[16:19]
	v_mfma_f32_16x16x32_bf16 v[190:193], v[124:127], v[198:201], v[8:11]
	v_mfma_f32_16x16x32_bf16 v[8:11], v[170:173], v[194:197], v[20:23]
	v_mfma_f32_16x16x32_bf16 v[170:173], v[174:177], v[198:201], v[8:11]
	s_setprio 0
	s_barrier
	s_nop 4
	ds_read_b128 v[8:11], v144
	ds_read_b128 v[12:15], v144 offset:1024
	ds_read_b128 v[16:19], v144 offset:2048
	ds_read_b128 v[20:23], v144 offset:3072
	ds_read_b128 v[174:177], v145
	ds_read_b128 v[194:197], v145 offset:1024
	ds_read_b128 v[198:201], v145 offset:2048
	ds_read_b128 v[222:225], v145 offset:3072
	s_add_u32 s26, s28, 0x4000
	s_addc_u32 s27, s29, 0
	s_mov_b32 m0, s39
	ds_read_b128 v[24:27], v143 offset:32768
	ds_read_b128 v[28:31], v143 offset:33792
	ds_read_b128 v[60:63], v143 offset:34816
	ds_read_b128 v[226:229], v143 offset:35840
	ds_read_b128 v[230:233], v143 offset:36864
	ds_read_b128 v[234:237], v143 offset:37888
	ds_read_b128 v[238:241], v143 offset:38912
	ds_read_b128 v[242:245], v143 offset:39936
	global_load_lds_dwordx4 v134, s[26:27]
	v_lshl_add_u64 v[88:89], s[26:27], 0, v[130:131]
	s_mov_b32 m0, s40
	s_nop 0
	global_load_lds_dwordx4 v[88:89], off
	s_waitcnt vmcnt(8)
	s_waitcnt lgkmcnt(0)
	s_barrier
; #define PG8_STAGE(bufoff, gbase, voff) do { _Pragma("unroll") for (int _i = 0; _i < 2; ++_i) \
;         __builtin_amdgcn_global_load_lds((const unsigned*)((const char*)(gbase) + (voff)[_i]), (PG8_LAS unsigned*)(lds + (bufoff) + ldsw + _i * 8192), 16, 0, 0); } while (0)
; #define PG8_LDA(dst, b, h) do { _Pragma("unroll") for (int m = 0; m < 4; ++m) _Pragma("unroll") for (int k = 0; k < 2; ++k) dst[m][k] = *(const PG8_LAS bf16x8*)(lds + PG8_SA(b, h) + aoff + m * 2048 + k * 1024); } while (0)
; #define PG8_MMA(ai, bj, At, Bt) do { __builtin_amdgcn_s_setprio(1); _Pragma("unroll") for (int m = 0; m < 4; ++m) _Pragma("unroll") for (int n = 0; n < 2; ++n) _Pragma("unroll") for (int k = 0; k < 2; ++k) \
;         acc[ai][bj][m][n] = __builtin_amdgcn_mfma_f32_16x16x32_bf16(Bt[n][k], At[m][k], acc[ai][bj][m][n], 0, 0, 0); __builtin_amdgcn_s_setprio(0); } while (0)
; #define PG8_WAIT_V(n) asm volatile("s_waitcnt vmcnt(" #n ")" ::: "memory")
; #define PG8_WAIT_L(n) asm volatile("s_waitcnt lgkmcnt(" #n ")" ::: "memory")
; #define PG8_BAR __builtin_amdgcn_s_barrier()
; #define PG8_SCHED __builtin_amdgcn_sched_barrier(0)
;     ...
;             PG8_WAIT_V(8); PG8_WAIT_L(0); PG8_BAR; PG8_MMA(0, 0, At, B0); PG8_MMA(0, 1, At, B1); PG8_BAR; PG8_SCHED;
;             PG8_LDA(At, 1, 1); PG8_STAGE(PG8_SB(1, 0), b3, voffB); PG8_STAGE(PG8_SB(1, 1), b3 + hstepB, voffB); PG8_STAGE(PG8_SA(1, 0), a3, voffA);
;             PG8_WAIT_V(8); PG8_WAIT_L(0); PG8_BAR; PG8_MMA(1, 0, At, B0); PG8_MMA(1, 1, At, B1); PG8_BAR; PG8_SCHED;
;     ...
;         if constexpr (ALIGN_EPI) { if (wr == 0) PG8_BAR; }
	s_setprio 1
	s_waitcnt lgkmcnt(0)
	v_mfma_f32_16x16x32_bf16 v[64:67], v[8:11], v[24:27], v[64:67]
	v_mfma_f32_16x16x32_bf16 v[124:127], v[12:15], v[28:31], v[64:67]
	v_mfma_f32_16x16x32_bf16 v[64:67], v[16:19], v[24:27], v[68:71]
	v_mfma_f32_16x16x32_bf16 v[120:123], v[20:23], v[28:31], v[64:67]
	v_mfma_f32_16x16x32_bf16 v[64:67], v[8:11], v[60:63], v[72:75]
	v_mfma_f32_16x16x32_bf16 v[108:111], v[12:15], v[226:229], v[64:67]
	v_mfma_f32_16x16x32_bf16 v[64:67], v[16:19], v[60:63], v[76:79]
	v_mfma_f32_16x16x32_bf16 v[104:107], v[20:23], v[226:229], v[64:67]
	v_mfma_f32_16x16x32_bf16 v[64:67], v[8:11], v[230:233], v[80:83]
	v_mfma_f32_16x16x32_bf16 v[92:95], v[12:15], v[234:237], v[64:67]
	v_mfma_f32_16x16x32_bf16 v[64:67], v[16:19], v[230:233], v[84:87]
	v_mfma_f32_16x16x32_bf16 v[88:91], v[20:23], v[234:237], v[64:67]
	v_mfma_f32_16x16x32_bf16 v[64:67], v[8:11], v[238:241], v[210:213]
	v_mfma_f32_16x16x32_bf16 v[76:79], v[12:15], v[242:245], v[64:67]
	v_mfma_f32_16x16x32_bf16 v[64:67], v[16:19], v[238:241], v[214:217]
	v_mfma_f32_16x16x32_bf16 v[72:75], v[20:23], v[242:245], v[64:67]
	s_setprio 0
	s_setprio 1
	v_mfma_f32_16x16x32_bf16 v[64:67], v[174:177], v[24:27], v[96:99]
	v_mfma_f32_16x16x32_bf16 v[24:27], v[198:201], v[24:27], v[32:35]
	v_mfma_f32_16x16x32_bf16 v[112:115], v[222:225], v[28:31], v[24:27]
	v_mfma_f32_16x16x32_bf16 v[24:27], v[174:177], v[60:63], v[36:39]
	v_mfma_f32_16x16x32_bf16 v[100:103], v[194:197], v[226:229], v[24:27]
	v_mfma_f32_16x16x32_bf16 v[24:27], v[198:201], v[60:63], v[40:43]
	v_mfma_f32_16x16x32_bf16 v[96:99], v[222:225], v[226:229], v[24:27]
	v_mfma_f32_16x16x32_bf16 v[24:27], v[174:177], v[230:233], v[44:47]
	v_mfma_f32_16x16x32_bf16 v[84:87], v[194:197], v[234:237], v[24:27]
	v_mfma_f32_16x16x32_bf16 v[24:27], v[198:201], v[230:233], v[48:51]
	v_mfma_f32_16x16x32_bf16 v[80:83], v[222:225], v[234:237], v[24:27]
	v_mfma_f32_16x16x32_bf16 v[24:27], v[174:177], v[238:241], v[52:55]
	v_mfma_f32_16x16x32_bf16 v[60:63], v[194:197], v[242:245], v[24:27]
	v_mfma_f32_16x16x32_bf16 v[24:27], v[198:201], v[238:241], v[56:59]
	v_mfma_f32_16x16x32_bf16 v[116:119], v[194:197], v[28:31], v[64:67]
	v_mfma_f32_16x16x32_bf16 v[56:59], v[222:225], v[242:245], v[24:27]
	s_setprio 0
	s_barrier
	s_mov_b32 m0, s53
	s_nop 2
	v_lshl_add_u64 v[24:25], v[246:247], 0, s[12:13]
	s_add_u32 s24, s24, 0x10080
	ds_read_b128 v[32:35], v143 offset:49152
	ds_read_b128 v[36:39], v143 offset:50176
	ds_read_b128 v[210:213], v143 offset:51200
	ds_read_b128 v[214:217], v143 offset:52224
	ds_read_b128 v[226:229], v143 offset:53248
	ds_read_b128 v[230:233], v143 offset:54272
	ds_read_b128 v[234:237], v143 offset:55296
	ds_read_b128 v[238:241], v143 offset:56320
	global_load_lds_dwordx4 v[24:25], off
	v_lshl_add_u64 v[24:25], v[248:249], 0, s[12:13]
	s_mov_b32 m0, s54
	s_addc_u32 s25, s25, 0
	global_load_lds_dwordx4 v[24:25], off
	s_mov_b32 m0, s55
	s_nop 0
	global_load_lds_dwordx4 v132, s[24:25]
	s_mov_b32 m0, s56
	s_nop 0
	global_load_lds_dwordx4 v128, s[24:25]
	s_mov_b32 m0, s42
	s_nop 0
	global_load_lds_dwordx4 v134, s[30:31]
	v_lshl_add_u64 v[24:25], s[30:31], 0, v[130:131]
	s_mov_b32 m0, s43
	s_nop 0
	global_load_lds_dwordx4 v[24:25], off
	s_waitcnt vmcnt(8)
	s_waitcnt lgkmcnt(0)
	s_barrier
	s_setprio 1
	s_waitcnt lgkmcnt(0)
	v_mfma_f32_16x16x32_bf16 v[24:27], v[8:11], v[32:35], v[146:149]
	v_mfma_f32_16x16x32_bf16 v[68:71], v[12:15], v[36:39], v[24:27]
	v_mfma_f32_16x16x32_bf16 v[24:27], v[16:19], v[32:35], v[150:153]
	v_mfma_f32_16x16x32_bf16 v[64:67], v[20:23], v[36:39], v[24:27]
	v_mfma_f32_16x16x32_bf16 v[24:27], v[8:11], v[210:213], v[154:157]
	v_mfma_f32_16x16x32_bf16 v[44:47], v[12:15], v[214:217], v[24:27]
	v_mfma_f32_16x16x32_bf16 v[24:27], v[16:19], v[210:213], v[158:161]
	v_mfma_f32_16x16x32_bf16 v[40:43], v[20:23], v[214:217], v[24:27]
	v_mfma_f32_16x16x32_bf16 v[24:27], v[8:11], v[226:229], v[162:165]
	v_mfma_f32_16x16x32_bf16 v[28:31], v[12:15], v[230:233], v[24:27]
	v_mfma_f32_16x16x32_bf16 v[0:3], v[8:11], v[234:237], v[0:3]
	v_mfma_f32_16x16x32_bf16 v[12:15], v[12:15], v[238:241], v[0:3]
	v_mfma_f32_16x16x32_bf16 v[24:27], v[16:19], v[226:229], v[166:169]
	v_mfma_f32_16x16x32_bf16 v[24:27], v[20:23], v[230:233], v[24:27]
	v_mfma_f32_16x16x32_bf16 v[0:3], v[16:19], v[234:237], v[4:7]
	v_mfma_f32_16x16x32_bf16 v[8:11], v[20:23], v[238:241], v[0:3]
	s_setprio 0
	s_setprio 1
	v_mfma_f32_16x16x32_bf16 v[0:3], v[174:177], v[32:35], v[202:205]
	v_mfma_f32_16x16x32_bf16 v[52:55], v[194:197], v[36:39], v[0:3]
	v_mfma_f32_16x16x32_bf16 v[0:3], v[198:201], v[32:35], v[206:209]
	v_mfma_f32_16x16x32_bf16 v[48:51], v[222:225], v[36:39], v[0:3]
	v_mfma_f32_16x16x32_bf16 v[0:3], v[174:177], v[210:213], v[218:221]
	v_mfma_f32_16x16x32_bf16 v[36:39], v[194:197], v[214:217], v[0:3]
	v_mfma_f32_16x16x32_bf16 v[0:3], v[198:201], v[210:213], v[178:181]
	v_mfma_f32_16x16x32_bf16 v[32:35], v[222:225], v[214:217], v[0:3]
	v_mfma_f32_16x16x32_bf16 v[0:3], v[174:177], v[226:229], v[182:185]
	v_mfma_f32_16x16x32_bf16 v[20:23], v[194:197], v[230:233], v[0:3]
	v_mfma_f32_16x16x32_bf16 v[0:3], v[198:201], v[226:229], v[186:189]
	v_mfma_f32_16x16x32_bf16 v[16:19], v[222:225], v[230:233], v[0:3]
	v_mfma_f32_16x16x32_bf16 v[0:3], v[174:177], v[234:237], v[190:193]
	v_mfma_f32_16x16x32_bf16 v[4:7], v[194:197], v[238:241], v[0:3]
	v_mfma_f32_16x16x32_bf16 v[0:3], v[198:201], v[234:237], v[170:173]
	v_mfma_f32_16x16x32_bf16 v[0:3], v[222:225], v[238:241], v[0:3]
	s_setprio 0
	s_barrier
	s_and_b64 vcc, exec, s[0:1]
	s_cbranch_vccnz .LBB0_99
	s_barrier

; #define PG8_STAGE(bufoff, gbase, voff) do { _Pragma("unroll") for (int _i = 0; _i < 2; ++_i) \
;         __builtin_amdgcn_global_load_lds((const unsigned*)((const char*)(gbase) + (voff)[_i]), (PG8_LAS unsigned*)(lds + (bufoff) + ldsw + _i * 8192), 16, 0, 0); } while (0)
; #define PG8_LDA(dst, b, h) do { _Pragma("unroll") for (int m = 0; m < 4; ++m) _Pragma("unroll") for (int k = 0; k < 2; ++k) dst[m][k] = *(const PG8_LAS bf16x8*)(lds + PG8_SA(b, h) + aoff + m * 2048 + k * 1024); } while (0)
; #define PG8_LDB(dst, b, h) do { _Pragma("unroll") for (int n = 0; n < 2; ++n) _Pragma("unroll") for (int k = 0; k < 2; ++k) dst[n][k] = *(const PG8_LAS bf16x8*)(lds + PG8_SB(b, h) + boff + n * 2048 + k * 1024); } while (0)
; #define PG8_MMA(ai, bj, At, Bt) do { __builtin_amdgcn_s_setprio(1); _Pragma("unroll") for (int m = 0; m < 4; ++m) _Pragma("unroll") for (int n = 0; n < 2; ++n) _Pragma("unroll") for (int k = 0; k < 2; ++k) \
;         acc[ai][bj][m][n] = __builtin_amdgcn_mfma_f32_16x16x32_bf16(Bt[n][k], At[m][k], acc[ai][bj][m][n], 0, 0, 0); __builtin_amdgcn_s_setprio(0); } while (0)
; #define PG8_WAIT_V(n) asm volatile("s_waitcnt vmcnt(" #n ")" ::: "memory")
; #define PG8_WAIT_L(n) asm volatile("s_waitcnt lgkmcnt(" #n ")" ::: "memory")
; #define PG8_BAR __builtin_amdgcn_s_barrier()
; #define PG8_SCHED __builtin_amdgcn_sched_barrier(0)
;     ...
;         for (int t = 0; t < nt; t += 2) {
;             const bool last = (t == nt - 2);
;             const char* a1 = cA + (ptrdiff_t)(t + 1) * kstepA;
;             const char* a2 = last ? nA : cA + (ptrdiff_t)(t + 2) * kstepA; const char* b2 = last ? nB : cB + (ptrdiff_t)(t + 2) * kstep;
;             const char* a3 = a2 + kstepA; const char* b3 = b2 + kstep;
;             if (last && has_next) S.a_ready(nxt);
;             if constexpr (SP2) {
;             PG8_LDB(B0, 0, 0); PG8_LDB(B1, 0, 1); PG8_SCHED; PG8_LDA(At, 0, 0); PG8_STAGE(PG8_SA(1, 1), a1 + hstepA, voffA);
;             PG8_WAIT_V(8); PG8_WAIT_L(0); PG8_BAR; PG8_MMA(0, 0, At, B0); PG8_MMA(0, 1, At, B1); PG8_BAR; PG8_SCHED;
;             PG8_LDA(At, 0, 1); PG8_STAGE(PG8_SB(0, 0), b2, voffB); PG8_STAGE(PG8_SB(0, 1), b2 + hstepB, voffB); PG8_STAGE(PG8_SA(0, 0), a2, voffA);
;             PG8_WAIT_V(8); PG8_WAIT_L(0); PG8_BAR; PG8_MMA(1, 0, At, B0); PG8_MMA(1, 1, At, B1); PG8_BAR; PG8_SCHED;
.LBB0_328:
	s_add_u32 s65, s6, 0x4000
	s_addc_u32 s66, s7, 0
	s_cmp_eq_u32 vcc_lo, 28
	s_cselect_b32 s90, s54, s65
	s_cselect_b32 s91, s29, s66
	s_cselect_b32 s88, s55, s56
	s_cselect_b32 s89, s31, s57
	s_add_u32 s86, s90, 0x8000
	s_addc_u32 s87, s91, 0
	s_add_i32 s65, 0, 0x10000
	s_add_i32 s66, 0, 0x14000
	v_add_u32_e32 v22, s65, v182
	v_add_u32_e32 v54, s66, v182
	ds_read_b128 v[10:13], v22
	ds_read_b128 v[14:17], v22 offset:1024
	ds_read_b128 v[18:21], v22 offset:2048
	ds_read_b128 v[22:25], v22 offset:3072
	ds_read_b128 v[26:29], v54
	ds_read_b128 v[38:41], v54 offset:1024
	ds_read_b128 v[50:53], v54 offset:2048
	ds_read_b128 v[54:57], v54 offset:3072
	s_add_i32 m0, s51, 0xc000
	ds_read_b128 v[172:175], v183
	ds_read_b128 v[176:179], v183 offset:1024
	ds_read_b128 v[184:187], v183 offset:2048
	ds_read_b128 v[188:191], v183 offset:3072
	ds_read_b128 v[192:195], v183 offset:4096
	ds_read_b128 v[196:199], v183 offset:5120
	ds_read_b128 v[200:203], v183 offset:6144
	ds_read_b128 v[204:207], v183 offset:7168
	global_load_lds_dwordx4 v168, s[6:7]
	s_add_i32 m0, s51, 0xe000
	s_nop 0
	global_load_lds_dwordx4 v170, s[6:7]
	s_waitcnt vmcnt(8)
	s_waitcnt lgkmcnt(0)
	s_barrier
	s_setprio 1
	s_waitcnt lgkmcnt(0)
	v_mfma_f32_16x16x32_bf16 v[158:161], v[10:13], v[172:175], v[158:161]
	v_mfma_f32_16x16x32_bf16 v[158:161], v[14:17], v[176:179], v[158:161]
	v_mfma_f32_16x16x32_bf16 v[154:157], v[18:21], v[172:175], v[154:157]
	v_mfma_f32_16x16x32_bf16 v[154:157], v[22:25], v[176:179], v[154:157]
	v_mfma_f32_16x16x32_bf16 v[142:145], v[10:13], v[184:187], v[142:145]
	v_mfma_f32_16x16x32_bf16 v[142:145], v[14:17], v[188:191], v[142:145]
	v_mfma_f32_16x16x32_bf16 v[138:141], v[18:21], v[184:187], v[138:141]
	v_mfma_f32_16x16x32_bf16 v[138:141], v[22:25], v[188:191], v[138:141]
	v_mfma_f32_16x16x32_bf16 v[126:129], v[10:13], v[192:195], v[126:129]
	v_mfma_f32_16x16x32_bf16 v[126:129], v[14:17], v[196:199], v[126:129]
	v_mfma_f32_16x16x32_bf16 v[122:125], v[18:21], v[192:195], v[122:125]
	v_mfma_f32_16x16x32_bf16 v[122:125], v[22:25], v[196:199], v[122:125]
	v_mfma_f32_16x16x32_bf16 v[110:113], v[10:13], v[200:203], v[110:113]
	v_mfma_f32_16x16x32_bf16 v[110:113], v[14:17], v[204:207], v[110:113]
	v_mfma_f32_16x16x32_bf16 v[106:109], v[18:21], v[200:203], v[106:109]
	v_mfma_f32_16x16x32_bf16 v[106:109], v[22:25], v[204:207], v[106:109]
	s_setprio 0
	s_setprio 1
	v_mfma_f32_16x16x32_bf16 v[150:153], v[26:29], v[172:175], v[150:153]
	v_mfma_f32_16x16x32_bf16 v[150:153], v[38:41], v[176:179], v[150:153]
	v_mfma_f32_16x16x32_bf16 v[146:149], v[50:53], v[172:175], v[146:149]
	v_mfma_f32_16x16x32_bf16 v[146:149], v[54:57], v[176:179], v[146:149]
	v_mfma_f32_16x16x32_bf16 v[134:137], v[26:29], v[184:187], v[134:137]
	v_mfma_f32_16x16x32_bf16 v[134:137], v[38:41], v[188:191], v[134:137]
	v_mfma_f32_16x16x32_bf16 v[130:133], v[50:53], v[184:187], v[130:133]
	v_mfma_f32_16x16x32_bf16 v[130:133], v[54:57], v[188:191], v[130:133]
	v_mfma_f32_16x16x32_bf16 v[118:121], v[26:29], v[192:195], v[118:121]
	v_mfma_f32_16x16x32_bf16 v[118:121], v[38:41], v[196:199], v[118:121]
	v_mfma_f32_16x16x32_bf16 v[114:117], v[50:53], v[192:195], v[114:117]
	v_mfma_f32_16x16x32_bf16 v[114:117], v[54:57], v[196:199], v[114:117]
	v_mfma_f32_16x16x32_bf16 v[102:105], v[26:29], v[200:203], v[102:105]
	v_mfma_f32_16x16x32_bf16 v[102:105], v[38:41], v[204:207], v[102:105]
	v_mfma_f32_16x16x32_bf16 v[98:101], v[50:53], v[200:203], v[98:101]
	v_mfma_f32_16x16x32_bf16 v[98:101], v[54:57], v[204:207], v[98:101]
	s_setprio 0
	s_barrier
	s_add_i32 s65, s65, s2
	s_mov_b32 m0, s65
	ds_read_b128 v[172:175], v183 offset:16384
	ds_read_b128 v[176:179], v183 offset:17408
	ds_read_b128 v[184:187], v183 offset:18432
	ds_read_b128 v[188:191], v183 offset:19456
	ds_read_b128 v[192:195], v183 offset:20480
	ds_read_b128 v[196:199], v183 offset:21504
	ds_read_b128 v[200:203], v183 offset:22528
	ds_read_b128 v[204:207], v183 offset:23552
	global_load_lds_dwordx4 v0, s[88:89]
	s_add_i32 m0, s65, 0x2000
	s_add_u32 s96, s88, 0x4000
	s_addc_u32 s97, s89, 0
	s_add_i32 s65, s66, s2
	global_load_lds_dwordx4 v162, s[88:89]
	s_mov_b32 m0, s65
	s_nop 0
	global_load_lds_dwordx4 v0, s[96:97]
	s_add_i32 m0, s65, 0x2000
	s_nop 0
	global_load_lds_dwordx4 v162, s[96:97]
	s_mov_b32 m0, s51
	s_nop 0
	global_load_lds_dwordx4 v166, s[90:91]
	s_mov_b32 m0, s92
	s_nop 0
	global_load_lds_dwordx4 v164, s[90:91]
	s_waitcnt vmcnt(8)
	s_waitcnt lgkmcnt(0)
	s_barrier
	s_setprio 1
	s_waitcnt lgkmcnt(0)
	v_mfma_f32_16x16x32_bf16 v[94:97], v[10:13], v[172:175], v[94:97]
	v_mfma_f32_16x16x32_bf16 v[94:97], v[14:17], v[176:179], v[94:97]
	v_mfma_f32_16x16x32_bf16 v[90:93], v[18:21], v[172:175], v[90:93]
	v_mfma_f32_16x16x32_bf16 v[90:93], v[22:25], v[176:179], v[90:93]
	v_mfma_f32_16x16x32_bf16 v[78:81], v[10:13], v[184:187], v[78:81]
	v_mfma_f32_16x16x32_bf16 v[78:81], v[14:17], v[188:191], v[78:81]
	v_mfma_f32_16x16x32_bf16 v[74:77], v[18:21], v[184:187], v[74:77]
	v_mfma_f32_16x16x32_bf16 v[74:77], v[22:25], v[188:191], v[74:77]
	v_mfma_f32_16x16x32_bf16 v[62:65], v[10:13], v[192:195], v[62:65]
	v_mfma_f32_16x16x32_bf16 v[62:65], v[14:17], v[196:199], v[62:65]
	v_mfma_f32_16x16x32_bf16 v[58:61], v[18:21], v[192:195], v[58:61]
	v_mfma_f32_16x16x32_bf16 v[58:61], v[22:25], v[196:199], v[58:61]
	v_mfma_f32_16x16x32_bf16 v[10:13], v[10:13], v[200:203], v[34:37]
	v_mfma_f32_16x16x32_bf16 v[10:13], v[14:17], v[204:207], v[10:13]
	v_mfma_f32_16x16x32_bf16 v[14:17], v[18:21], v[200:203], v[30:33]
	v_mfma_f32_16x16x32_bf16 v[14:17], v[22:25], v[204:207], v[14:17]
	s_setprio 0
	s_setprio 1
	v_mfma_f32_16x16x32_bf16 v[30:33], v[26:29], v[184:187], v[70:73]
	v_mfma_f32_16x16x32_bf16 v[70:73], v[38:41], v[188:191], v[30:33]
	v_mfma_f32_16x16x32_bf16 v[30:33], v[50:53], v[184:187], v[66:69]
	v_mfma_f32_16x16x32_bf16 v[66:69], v[54:57], v[188:191], v[30:33]
	v_mfma_f32_16x16x32_bf16 v[30:33], v[26:29], v[192:195], v[46:49]
	v_mfma_f32_16x16x32_bf16 v[46:49], v[38:41], v[196:199], v[30:33]
	v_mfma_f32_16x16x32_bf16 v[30:33], v[50:53], v[192:195], v[42:45]
	v_mfma_f32_16x16x32_bf16 v[42:45], v[54:57], v[196:199], v[30:33]
	v_mfma_f32_16x16x32_bf16 v[6:9], v[26:29], v[200:203], v[6:9]
	v_mfma_f32_16x16x32_bf16 v[6:9], v[38:41], v[204:207], v[6:9]
	v_mfma_f32_16x16x32_bf16 v[2:5], v[50:53], v[200:203], v[2:5]
	v_mfma_f32_16x16x32_bf16 v[2:5], v[54:57], v[204:207], v[2:5]
	v_mfma_f32_16x16x32_bf16 v[18:21], v[26:29], v[172:175], v[86:89]
	v_mfma_f32_16x16x32_bf16 v[18:21], v[38:41], v[176:179], v[18:21]
	v_mfma_f32_16x16x32_bf16 v[22:25], v[50:53], v[172:175], v[82:85]
	v_mfma_f32_16x16x32_bf16 v[22:25], v[54:57], v[176:179], v[22:25]
	s_setprio 0
	s_barrier
; #define PG8_STAGE(bufoff, gbase, voff) do { _Pragma("unroll") for (int _i = 0; _i < 2; ++_i) \
;         __builtin_amdgcn_global_load_lds((const unsigned*)((const char*)(gbase) + (voff)[_i]), (PG8_LAS unsigned*)(lds + (bufoff) + ldsw + _i * 8192), 16, 0, 0); } while (0)
; #define PG8_LDA(dst, b, h) do { _Pragma("unroll") for (int m = 0; m < 4; ++m) _Pragma("unroll") for (int k = 0; k < 2; ++k) dst[m][k] = *(const PG8_LAS bf16x8*)(lds + PG8_SA(b, h) + aoff + m * 2048 + k * 1024); } while (0)
; #define PG8_LDB(dst, b, h) do { _Pragma("unroll") for (int n = 0; n < 2; ++n) _Pragma("unroll") for (int k = 0; k < 2; ++k) dst[n][k] = *(const PG8_LAS bf16x8*)(lds + PG8_SB(b, h) + boff + n * 2048 + k * 1024); } while (0)
; #define PG8_MMA(ai, bj, At, Bt) do { __builtin_amdgcn_s_setprio(1); _Pragma("unroll") for (int m = 0; m < 4; ++m) _Pragma("unroll") for (int n = 0; n < 2; ++n) _Pragma("unroll") for (int k = 0; k < 2; ++k) \
;         acc[ai][bj][m][n] = __builtin_amdgcn_mfma_f32_16x16x32_bf16(Bt[n][k], At[m][k], acc[ai][bj][m][n], 0, 0, 0); __builtin_amdgcn_s_setprio(0); } while (0)
; #define PG8_WAIT_V(n) asm volatile("s_waitcnt vmcnt(" #n ")" ::: "memory")
; #define PG8_WAIT_L(n) asm volatile("s_waitcnt lgkmcnt(" #n ")" ::: "memory")
; #define PG8_BAR __builtin_amdgcn_s_barrier()
; #define PG8_SCHED __builtin_amdgcn_sched_barrier(0)
;     ...
;             PG8_LDB(B0, 1, 0); PG8_LDB(B1, 1, 1); PG8_SCHED; PG8_LDA(At, 1, 0); PG8_STAGE(PG8_SA(0, 1), a2 + hstepA, voffA);
;             PG8_WAIT_V(8); PG8_WAIT_L(0); PG8_BAR; PG8_MMA(0, 0, At, B0); PG8_MMA(0, 1, At, B1); PG8_BAR; PG8_SCHED;
;             PG8_LDA(At, 1, 1); PG8_STAGE(PG8_SB(1, 0), b3, voffB); PG8_STAGE(PG8_SB(1, 1), b3 + hstepB, voffB); PG8_STAGE(PG8_SA(1, 0), a3, voffA);
;             PG8_WAIT_V(8); PG8_WAIT_L(0); PG8_BAR; PG8_MMA(1, 0, At, B0); PG8_MMA(1, 1, At, B1); PG8_BAR; PG8_SCHED;
	s_add_i32 s65, 0, 0x18000
	v_add_u32_e32 v34, s65, v182
	s_add_i32 s66, 0, 0x1c000
	ds_read_b128 v[26:29], v34
	ds_read_b128 v[30:33], v34 offset:1024
	ds_read_b128 v[38:41], v34 offset:2048
	ds_read_b128 v[50:53], v34 offset:3072
	v_add_u32_e32 v34, s66, v182
	ds_read_b128 v[54:57], v34
	ds_read_b128 v[172:175], v34 offset:1024
	ds_read_b128 v[176:179], v34 offset:2048
	ds_read_b128 v[184:187], v34 offset:3072
	s_add_u32 s90, s90, 0x4000
	s_addc_u32 s91, s91, 0
	s_mov_b32 m0, s14
	ds_read_b128 v[34:37], v183 offset:32768
	ds_read_b128 v[82:85], v183 offset:33792
	ds_read_b128 v[86:89], v183 offset:34816
	ds_read_b128 v[188:191], v183 offset:35840
	ds_read_b128 v[192:195], v183 offset:36864
	ds_read_b128 v[196:199], v183 offset:37888
	ds_read_b128 v[200:203], v183 offset:38912
	ds_read_b128 v[204:207], v183 offset:39936
	global_load_lds_dwordx4 v166, s[90:91]
	v_lshl_add_u64 v[208:209], s[90:91], 0, v[164:165]
	s_mov_b32 m0, s15
	s_nop 0
	global_load_lds_dwordx4 v[208:209], off
	s_waitcnt vmcnt(8)
	s_waitcnt lgkmcnt(0)
	s_barrier
	s_setprio 1
	s_waitcnt lgkmcnt(0)
	v_mfma_f32_16x16x32_bf16 v[158:161], v[26:29], v[34:37], v[158:161]
	v_mfma_f32_16x16x32_bf16 v[158:161], v[30:33], v[82:85], v[158:161]
	v_mfma_f32_16x16x32_bf16 v[154:157], v[38:41], v[34:37], v[154:157]
	v_mfma_f32_16x16x32_bf16 v[154:157], v[50:53], v[82:85], v[154:157]
	v_mfma_f32_16x16x32_bf16 v[142:145], v[26:29], v[86:89], v[142:145]
	v_mfma_f32_16x16x32_bf16 v[142:145], v[30:33], v[188:191], v[142:145]
	v_mfma_f32_16x16x32_bf16 v[138:141], v[38:41], v[86:89], v[138:141]
	v_mfma_f32_16x16x32_bf16 v[138:141], v[50:53], v[188:191], v[138:141]
	v_mfma_f32_16x16x32_bf16 v[126:129], v[26:29], v[192:195], v[126:129]
	v_mfma_f32_16x16x32_bf16 v[126:129], v[30:33], v[196:199], v[126:129]
	v_mfma_f32_16x16x32_bf16 v[122:125], v[38:41], v[192:195], v[122:125]
	v_mfma_f32_16x16x32_bf16 v[122:125], v[50:53], v[196:199], v[122:125]
	v_mfma_f32_16x16x32_bf16 v[110:113], v[26:29], v[200:203], v[110:113]
	v_mfma_f32_16x16x32_bf16 v[110:113], v[30:33], v[204:207], v[110:113]
	v_mfma_f32_16x16x32_bf16 v[106:109], v[38:41], v[200:203], v[106:109]
	v_mfma_f32_16x16x32_bf16 v[106:109], v[50:53], v[204:207], v[106:109]
	s_setprio 0
	s_setprio 1
	v_mfma_f32_16x16x32_bf16 v[150:153], v[54:57], v[34:37], v[150:153]
	v_mfma_f32_16x16x32_bf16 v[150:153], v[172:175], v[82:85], v[150:153]
	v_mfma_f32_16x16x32_bf16 v[34:37], v[176:179], v[34:37], v[146:149]
	v_mfma_f32_16x16x32_bf16 v[146:149], v[184:187], v[82:85], v[34:37]
	v_mfma_f32_16x16x32_bf16 v[34:37], v[54:57], v[86:89], v[134:137]
	v_mfma_f32_16x16x32_bf16 v[134:137], v[172:175], v[188:191], v[34:37]
	v_mfma_f32_16x16x32_bf16 v[34:37], v[176:179], v[86:89], v[130:133]
	v_mfma_f32_16x16x32_bf16 v[130:133], v[184:187], v[188:191], v[34:37]
	v_mfma_f32_16x16x32_bf16 v[34:37], v[54:57], v[192:195], v[118:121]
	v_mfma_f32_16x16x32_bf16 v[118:121], v[172:175], v[196:199], v[34:37]
	v_mfma_f32_16x16x32_bf16 v[34:37], v[176:179], v[192:195], v[114:117]
	v_mfma_f32_16x16x32_bf16 v[114:117], v[184:187], v[196:199], v[34:37]
	v_mfma_f32_16x16x32_bf16 v[34:37], v[54:57], v[200:203], v[102:105]
	v_mfma_f32_16x16x32_bf16 v[102:105], v[172:175], v[204:207], v[34:37]
	v_mfma_f32_16x16x32_bf16 v[34:37], v[176:179], v[200:203], v[98:101]
	v_mfma_f32_16x16x32_bf16 v[98:101], v[184:187], v[204:207], v[34:37]
	s_setprio 0
	s_barrier
	s_add_u32 s90, s88, 0x8000
	s_addc_u32 s91, s89, 0
	s_add_i32 s65, s65, s2
	s_nop 0
	s_mov_b32 m0, s65
	ds_read_b128 v[82:85], v183 offset:49152
	ds_read_b128 v[188:191], v183 offset:50176
	ds_read_b128 v[192:195], v183 offset:51200
	ds_read_b128 v[196:199], v183 offset:52224
	ds_read_b128 v[200:203], v183 offset:53248
	ds_read_b128 v[204:207], v183 offset:54272
	ds_read_b128 v[208:211], v183 offset:55296
	ds_read_b128 v[216:219], v183 offset:56320
	global_load_lds_dwordx4 v0, s[90:91]
	s_add_i32 m0, s65, 0x2000
	s_add_u32 s88, s88, 0xc000
	s_addc_u32 s89, s89, 0
	s_add_i32 s65, s66, s2
	global_load_lds_dwordx4 v162, s[90:91]
	s_mov_b32 m0, s65
	s_nop 0
	global_load_lds_dwordx4 v0, s[88:89]
	s_add_i32 m0, s65, 0x2000
	s_nop 0
	global_load_lds_dwordx4 v162, s[88:89]
	s_mov_b32 m0, s71
	s_nop 0
	global_load_lds_dwordx4 v166, s[86:87]
	v_lshl_add_u64 v[34:35], s[86:87], 0, v[164:165]
	s_mov_b32 m0, s80
	s_nop 0
	global_load_lds_dwordx4 v[34:35], off
	s_waitcnt vmcnt(8)
	s_waitcnt lgkmcnt(0)
	s_barrier
	s_setprio 1
	s_waitcnt lgkmcnt(0)
	v_mfma_f32_16x16x32_bf16 v[34:37], v[26:29], v[82:85], v[94:97]
	v_mfma_f32_16x16x32_bf16 v[94:97], v[30:33], v[188:191], v[34:37]
	v_mfma_f32_16x16x32_bf16 v[34:37], v[38:41], v[82:85], v[90:93]
	v_mfma_f32_16x16x32_bf16 v[90:93], v[50:53], v[188:191], v[34:37]
	v_mfma_f32_16x16x32_bf16 v[34:37], v[26:29], v[192:195], v[78:81]
	v_mfma_f32_16x16x32_bf16 v[78:81], v[30:33], v[196:199], v[34:37]
	v_mfma_f32_16x16x32_bf16 v[34:37], v[38:41], v[192:195], v[74:77]
	v_mfma_f32_16x16x32_bf16 v[74:77], v[50:53], v[196:199], v[34:37]
	v_mfma_f32_16x16x32_bf16 v[34:37], v[26:29], v[200:203], v[62:65]
	v_mfma_f32_16x16x32_bf16 v[62:65], v[30:33], v[204:207], v[34:37]
	v_mfma_f32_16x16x32_bf16 v[34:37], v[38:41], v[200:203], v[58:61]
	v_mfma_f32_16x16x32_bf16 v[58:61], v[50:53], v[204:207], v[34:37]
	v_mfma_f32_16x16x32_bf16 v[10:13], v[26:29], v[208:211], v[10:13]
	v_mfma_f32_16x16x32_bf16 v[34:37], v[30:33], v[216:219], v[10:13]
	v_mfma_f32_16x16x32_bf16 v[10:13], v[38:41], v[208:211], v[14:17]
	v_mfma_f32_16x16x32_bf16 v[30:33], v[50:53], v[216:219], v[10:13]
	s_setprio 0
	s_setprio 1
	v_mfma_f32_16x16x32_bf16 v[10:13], v[54:57], v[82:85], v[18:21]
	v_mfma_f32_16x16x32_bf16 v[86:89], v[172:175], v[188:191], v[10:13]
	v_mfma_f32_16x16x32_bf16 v[10:13], v[176:179], v[82:85], v[22:25]
	v_mfma_f32_16x16x32_bf16 v[82:85], v[184:187], v[188:191], v[10:13]
	v_mfma_f32_16x16x32_bf16 v[10:13], v[54:57], v[192:195], v[70:73]
	v_mfma_f32_16x16x32_bf16 v[70:73], v[172:175], v[196:199], v[10:13]
	v_mfma_f32_16x16x32_bf16 v[10:13], v[176:179], v[192:195], v[66:69]
	v_mfma_f32_16x16x32_bf16 v[66:69], v[184:187], v[196:199], v[10:13]
	v_mfma_f32_16x16x32_bf16 v[10:13], v[54:57], v[200:203], v[46:49]
	v_mfma_f32_16x16x32_bf16 v[46:49], v[172:175], v[204:207], v[10:13]
	v_mfma_f32_16x16x32_bf16 v[10:13], v[176:179], v[200:203], v[42:45]
	v_mfma_f32_16x16x32_bf16 v[42:45], v[184:187], v[204:207], v[10:13]
	v_mfma_f32_16x16x32_bf16 v[6:9], v[54:57], v[208:211], v[6:9]
	v_mfma_f32_16x16x32_bf16 v[6:9], v[172:175], v[216:219], v[6:9]
	v_mfma_f32_16x16x32_bf16 v[2:5], v[176:179], v[208:211], v[2:5]
	v_mfma_f32_16x16x32_bf16 v[2:5], v[184:187], v[216:219], v[2:5]
	s_setprio 0
	s_barrier
	s_add_i32 vcc_lo, vcc_lo, 2
	s_add_u32 s6, s6, 0x10000
	s_addc_u32 s7, s7, 0
	s_add_u32 s56, s56, 0x10000
	s_addc_u32 s57, s57, 0
	s_cmp_gt_u32 vcc_lo, 29
	s_cbranch_scc0 .LBB0_328
	s_and_b64 vcc, exec, s[26:27]
	s_cbranch_vccz .LBB0_331
	s_barrier
